# v181 with the two bj bounce-ins of each P4 epilogue row pipelined behind one LDS wait
# baseline (speedup 1.0000x reference)
; __device__ __forceinline__ u32x4 pack8(const float (&f)[8]) { u32x4 w; w.x = cvt_pk_bf16(f[0], f[1]); w.y = cvt_pk_bf16(f[2], f[3]); w.z = cvt_pk_bf16(f[4], f[5]); w.w = cvt_pk_bf16(f[6], f[7]); return w; }
;     __device__ __forceinline__ void operator()(const f32x4 (&acc)[2][2][4][2], const Unit& u, int wr, int wc, int fr, int fq) const {
;         const int row0 = u.pm * BM + wr * 64 + fr, col0 = u.pn * BM + wc * 32 + 8 * fq;
; #pragma unroll
;         for (int ai = 0; ai < 2; ++ai)
; #pragma unroll
;             for (int m = 0; m < 4; ++m) { const int row = row0 + ai * HALF + m * 16; const size_t idx = (size_t)row * 1024 + col0; float ss = 0.f;
; #pragma unroll
;                 for (int bj = 0; bj < 2; ++bj) { const f32x4 x0 = __builtin_nontemporal_load((const f32x4*)(x + idx + bj * HALF)), x1 = __builtin_nontemporal_load((const f32x4*)(x + idx + bj * HALF + 4));
;                     const f32x4 h0 = x0 + acc[ai][bj][m][0], h1v = x1 + acc[ai][bj][m][1];
;                     float f[8] = {h0[0], h0[1], h0[2], h0[3], h1v[0], h1v[1], h1v[2], h1v[3]};
; #pragma unroll
;                     for (int e = 0; e < 8; ++e) ss += f[e] * f[e];
;                     *(u32x4*)(h1b + idx + bj * HALF) = pack8(f); }
;                 ss += __shfl_xor(ss, 16); ss += __shfl_xor(ss, 32);
;                 if (fq == 0) atomicAdd(ssq + row, ss); }
.LBB0_648:
	v_lshl_add_u32 v148, s44, 8, v150
	v_lshlrev_b32_e32 v149, 2, v148
	v_bfe_u32 v236, v150, 6, 1
	v_bfe_u32 v237, v152, 5, 2
	v_lshl_or_b32 v236, v236, 2, v237
	v_mul_u32_u24_e32 v236, 0x500, v236
	v_add_u32_e32 v236, 0x20000, v236
	v_and_b32_e32 v237, 7, v150
	v_bfe_u32 v238, v152, 3, 2
	v_lshlrev_b32_e32 v238, 1, v238
	v_xor_b32_e32 v239, v238, v237
	v_lshlrev_b32_e32 v239, 4, v239
	v_lshl_add_u32 v227, v237, 7, v239
	v_add_u32_e32 v227, v227, v236
	v_or_b32_e32 v238, 1, v238
	v_xor_b32_e32 v239, v238, v237
	v_lshlrev_b32_e32 v239, 4, v239
	v_lshl_add_u32 v228, v237, 7, v239
	v_add_u32_e32 v228, v228, v236
	v_lshrrev_b32_e32 v237, 3, v156
	v_and_b32_e32 v238, 7, v156
	v_xor_b32_e32 v239, v238, v237
	v_lshlrev_b32_e32 v239, 4, v239
	v_lshl_add_u32 v226, v237, 7, v239
	v_add_u32_e32 v226, v226, v236
	v_and_or_b32 v147, v150, -16, v237
	v_lshl_add_u32 v147, s44, 8, v147
	v_and_b32_e32 v239, 0xffffffe7, v152
	v_lshl_or_b32 v239, s46, 8, v239
	v_lshl_add_u32 v239, v238, 2, v239
	v_lshl_add_u32 v147, v147, 10, v239
	v_lshlrev_b32_e32 v147, 2, v147
	v_add_u32_e32 v144, 0x8000, v147
	v_and_b32_e32 v237, 15, v150
	v_mul_u32_u24_e32 v234, 0x50, v237
	v_bfe_u32 v238, v152, 3, 2
	v_lshl_add_u32 v234, v238, 4, v234
	v_add_u32_e32 v234, v234, v236
	v_lshrrev_b32_e32 v237, 2, v156
	v_and_b32_e32 v238, 3, v156
	v_mul_u32_u24_e32 v235, 0x50, v237
	v_lshl_add_u32 v235, v238, 4, v235
	v_add_u32_e32 v235, v235, v236
	v_and_or_b32 v145, v150, -16, v237
	v_lshl_add_u32 v145, s44, 8, v145
	v_and_b32_e32 v239, 0xffffffe7, v152
	v_lshl_or_b32 v239, s46, 8, v239
	v_lshl_add_u32 v239, v238, 3, v239
	v_lshl_add_u32 v145, v145, 10, v239
	v_lshlrev_b32_e32 v145, 1, v145
	s_mov_b32 s98, 0x00ff00ff
	s_mov_b32 s99, 0x00ff00ff
	s_mov_b32 s100, 0xff00ff00
	s_mov_b32 s101, 0xff00ff00
	global_load_dwordx4 v[158:161], v147, s[52:53] nt
	global_load_dwordx4 v[162:165], v144, s[52:53] nt
	global_load_dwordx4 v[166:169], v147, s[52:53] offset:512 nt
	global_load_dwordx4 v[170:173], v144, s[52:53] offset:512 nt
	v_add_u32_e32 v147, 0x10000, v147
	v_add_u32_e32 v144, 0x10000, v144
	global_load_dwordx4 v[174:177], v147, s[52:53] nt
	global_load_dwordx4 v[178:181], v144, s[52:53] nt
	global_load_dwordx4 v[182:185], v147, s[52:53] offset:512 nt
	global_load_dwordx4 v[186:189], v144, s[52:53] offset:512 nt
	v_add_u32_e32 v147, 0x10000, v147
	v_add_u32_e32 v144, 0x10000, v144
	global_load_dwordx4 v[190:193], v147, s[52:53] nt
	global_load_dwordx4 v[194:197], v144, s[52:53] nt
	global_load_dwordx4 v[198:201], v147, s[52:53] offset:512 nt
	global_load_dwordx4 v[206:209], v144, s[52:53] offset:512 nt
	v_add_u32_e32 v147, 0x10000, v147
	v_add_u32_e32 v144, 0x10000, v144
	global_load_dwordx4 v[210:213], v147, s[52:53] nt
	global_load_dwordx4 v[214:217], v144, s[52:53] nt
	global_load_dwordx4 v[218:221], v147, s[52:53] offset:512 nt
	global_load_dwordx4 v[222:225], v144, s[52:53] offset:512 nt
	v_add_u32_e32 v147, 0x50000, v147
	v_add_u32_e32 v144, 0x50000, v144
	s_waitcnt vmcnt(12)
	ds_write_b128 v226, v[158:161]
	s_mov_b64 exec, s[98:99]
	ds_read_b128 v[158:161], v227
	ds_read_b128 v[230:233], v228
	s_mov_b64 exec, -1
	ds_write_b128 v226, v[162:165]
	s_mov_b64 exec, s[100:101]
	ds_read_b128 v[158:161], v227
	ds_read_b128 v[230:233], v228
	s_mov_b64 exec, -1
	ds_write_b128 v226, v[166:169]
	s_mov_b64 exec, s[98:99]
	ds_read_b128 v[166:169], v227
	ds_read_b128 v[236:239], v228
	s_mov_b64 exec, -1
	ds_write_b128 v226, v[170:173]
	s_mov_b64 exec, s[100:101]
	ds_read_b128 v[166:169], v227
	ds_read_b128 v[236:239], v228
	s_mov_b64 exec, -1
	s_waitcnt lgkmcnt(6)
	v_pk_add_f32 v[124:125], v[124:125], v[158:159]
	v_pk_add_f32 v[126:127], v[126:127], v[160:161]
	v_pk_add_f32 v[120:121], v[120:121], v[230:231]
	v_pk_add_f32 v[122:123], v[122:123], v[232:233]
	s_waitcnt lgkmcnt(0)
	v_pk_add_f32 v[116:117], v[116:117], v[166:167]
	v_pk_add_f32 v[118:119], v[118:119], v[168:169]
	v_pk_add_f32 v[112:113], v[112:113], v[236:237]
	v_pk_add_f32 v[114:115], v[114:115], v[238:239]
	v_cvt_pk_bf16_f32 v158, v124, v125
	v_cvt_pk_bf16_f32 v159, v126, v127
	v_cvt_pk_bf16_f32 v160, v120, v121
	v_cvt_pk_bf16_f32 v161, v122, v123
	v_cvt_pk_bf16_f32 v166, v116, v117
	v_cvt_pk_bf16_f32 v167, v118, v119
	v_cvt_pk_bf16_f32 v168, v112, v113
	v_cvt_pk_bf16_f32 v169, v114, v115
	ds_write_b128 v234, v[158:161]
	ds_read_b128 v[158:161], v235
	ds_write_b128 v234, v[166:169]
	ds_read_b128 v[166:169], v235
	v_mul_f32_e32 v157, v124, v124
	v_fmac_f32_e32 v157, v125, v125
	v_fmac_f32_e32 v157, v126, v126
	v_fmac_f32_e32 v157, v127, v127
	v_fmac_f32_e32 v157, v120, v120
	v_fmac_f32_e32 v157, v121, v121
	v_fmac_f32_e32 v157, v122, v122
	v_fmac_f32_e32 v157, v123, v123
	v_fmac_f32_e32 v157, v116, v116
	v_fmac_f32_e32 v157, v117, v117
	v_fmac_f32_e32 v157, v118, v118
	v_fmac_f32_e32 v157, v119, v119
	v_fmac_f32_e32 v157, v112, v112
	v_fmac_f32_e32 v157, v113, v113
	v_fmac_f32_e32 v157, v114, v114
	v_fmac_f32_e32 v157, v115, v115
	s_waitcnt lgkmcnt(2)
	global_store_dwordx4 v145, v[158:161], s[8:9]
	s_waitcnt lgkmcnt(0)
	global_store_dwordx4 v145, v[166:169], s[8:9] offset:256
	v_add_u32_e32 v145, 0x8000, v145
	global_load_dwordx4 v[158:161], v147, s[52:53] nt
	global_load_dwordx4 v[162:165], v144, s[52:53] nt
	global_load_dwordx4 v[166:169], v147, s[52:53] offset:512 nt
	global_load_dwordx4 v[170:173], v144, s[52:53] offset:512 nt
	v_add_u32_e32 v147, 0x10000, v147
	v_add_u32_e32 v144, 0x10000, v144
	s_waitcnt vmcnt(14)
; __device__ __forceinline__ u32x4 pack8(const float (&f)[8]) { u32x4 w; w.x = cvt_pk_bf16(f[0], f[1]); w.y = cvt_pk_bf16(f[2], f[3]); w.z = cvt_pk_bf16(f[4], f[5]); w.w = cvt_pk_bf16(f[6], f[7]); return w; }
;     __device__ __forceinline__ void operator()(const f32x4 (&acc)[2][2][4][2], const Unit& u, int wr, int wc, int fr, int fq) const {
;         const int row0 = u.pm * BM + wr * 64 + fr, col0 = u.pn * BM + wc * 32 + 8 * fq;
; #pragma unroll
;         for (int ai = 0; ai < 2; ++ai)
; #pragma unroll
;             for (int m = 0; m < 4; ++m) { const int row = row0 + ai * HALF + m * 16; const size_t idx = (size_t)row * 1024 + col0; float ss = 0.f;
; #pragma unroll
;                 for (int bj = 0; bj < 2; ++bj) { const f32x4 x0 = __builtin_nontemporal_load((const f32x4*)(x + idx + bj * HALF)), x1 = __builtin_nontemporal_load((const f32x4*)(x + idx + bj * HALF + 4));
;                     const f32x4 h0 = x0 + acc[ai][bj][m][0], h1v = x1 + acc[ai][bj][m][1];
;                     float f[8] = {h0[0], h0[1], h0[2], h0[3], h1v[0], h1v[1], h1v[2], h1v[3]};
; #pragma unroll
;                     for (int e = 0; e < 8; ++e) ss += f[e] * f[e];
;                     *(u32x4*)(h1b + idx + bj * HALF) = pack8(f); }
;                 ss += __shfl_xor(ss, 16); ss += __shfl_xor(ss, 32);
;                 if (fq == 0) atomicAdd(ssq + row, ss); }
	ds_write_b128 v226, v[174:177]
	s_mov_b64 exec, s[98:99]
	ds_read_b128 v[174:177], v227
	ds_read_b128 v[230:233], v228
	s_mov_b64 exec, -1
	ds_write_b128 v226, v[178:181]
	s_mov_b64 exec, s[100:101]
	ds_read_b128 v[174:177], v227
	ds_read_b128 v[230:233], v228
	s_mov_b64 exec, -1
	ds_write_b128 v226, v[182:185]
	s_mov_b64 exec, s[98:99]
	ds_read_b128 v[182:185], v227
	ds_read_b128 v[236:239], v228
	s_mov_b64 exec, -1
	ds_write_b128 v226, v[186:189]
	s_mov_b64 exec, s[100:101]
	ds_read_b128 v[182:185], v227
	ds_read_b128 v[236:239], v228
	s_mov_b64 exec, -1
	s_waitcnt lgkmcnt(6)
	v_pk_add_f32 v[108:109], v[108:109], v[174:175]
	v_pk_add_f32 v[110:111], v[110:111], v[176:177]
	v_pk_add_f32 v[104:105], v[104:105], v[230:231]
	v_pk_add_f32 v[106:107], v[106:107], v[232:233]
	s_waitcnt lgkmcnt(0)
	v_pk_add_f32 v[100:101], v[100:101], v[182:183]
	v_pk_add_f32 v[102:103], v[102:103], v[184:185]
	v_pk_add_f32 v[96:97], v[96:97], v[236:237]
	v_pk_add_f32 v[98:99], v[98:99], v[238:239]
	v_cvt_pk_bf16_f32 v174, v108, v109
	v_cvt_pk_bf16_f32 v175, v110, v111
	v_cvt_pk_bf16_f32 v176, v104, v105
	v_cvt_pk_bf16_f32 v177, v106, v107
	v_cvt_pk_bf16_f32 v182, v100, v101
	v_cvt_pk_bf16_f32 v183, v102, v103
	v_cvt_pk_bf16_f32 v184, v96, v97
	v_cvt_pk_bf16_f32 v185, v98, v99
	ds_write_b128 v234, v[174:177]
	ds_read_b128 v[174:177], v235
	ds_write_b128 v234, v[182:185]
	ds_read_b128 v[182:185], v235
	v_mul_f32_e32 v202, v108, v108
	v_fmac_f32_e32 v202, v109, v109
	v_fmac_f32_e32 v202, v110, v110
	v_fmac_f32_e32 v202, v111, v111
	v_fmac_f32_e32 v202, v104, v104
	v_fmac_f32_e32 v202, v105, v105
	v_fmac_f32_e32 v202, v106, v106
	v_fmac_f32_e32 v202, v107, v107
	v_fmac_f32_e32 v202, v100, v100
	v_fmac_f32_e32 v202, v101, v101
	v_fmac_f32_e32 v202, v102, v102
	v_fmac_f32_e32 v202, v103, v103
	v_fmac_f32_e32 v202, v96, v96
	v_fmac_f32_e32 v202, v97, v97
	v_fmac_f32_e32 v202, v98, v98
	v_fmac_f32_e32 v202, v99, v99
	s_waitcnt lgkmcnt(2)
	global_store_dwordx4 v145, v[174:177], s[8:9]
	s_waitcnt lgkmcnt(0)
	global_store_dwordx4 v145, v[182:185], s[8:9] offset:256
	v_add_u32_e32 v145, 0x8000, v145
	global_load_dwordx4 v[174:177], v147, s[52:53] nt
	global_load_dwordx4 v[178:181], v144, s[52:53] nt
	global_load_dwordx4 v[182:185], v147, s[52:53] offset:512 nt
	global_load_dwordx4 v[186:189], v144, s[52:53] offset:512 nt
	v_add_u32_e32 v147, 0x10000, v147
	v_add_u32_e32 v144, 0x10000, v144
	s_waitcnt vmcnt(16)
	ds_write_b128 v226, v[190:193]
	s_mov_b64 exec, s[98:99]
	ds_read_b128 v[190:193], v227
	ds_read_b128 v[230:233], v228
	s_mov_b64 exec, -1
	ds_write_b128 v226, v[194:197]
	s_mov_b64 exec, s[100:101]
	ds_read_b128 v[190:193], v227
	ds_read_b128 v[230:233], v228
	s_mov_b64 exec, -1
	ds_write_b128 v226, v[198:201]
	s_mov_b64 exec, s[98:99]
	ds_read_b128 v[198:201], v227
	ds_read_b128 v[236:239], v228
	s_mov_b64 exec, -1
	ds_write_b128 v226, v[206:209]
	s_mov_b64 exec, s[100:101]
	ds_read_b128 v[198:201], v227
	ds_read_b128 v[236:239], v228
	s_mov_b64 exec, -1
	s_waitcnt lgkmcnt(6)
	v_pk_add_f32 v[92:93], v[92:93], v[190:191]
	v_pk_add_f32 v[94:95], v[94:95], v[192:193]
	v_pk_add_f32 v[88:89], v[88:89], v[230:231]
	v_pk_add_f32 v[90:91], v[90:91], v[232:233]
	s_waitcnt lgkmcnt(0)
	v_pk_add_f32 v[84:85], v[84:85], v[198:199]
	v_pk_add_f32 v[86:87], v[86:87], v[200:201]
	v_pk_add_f32 v[80:81], v[80:81], v[236:237]
	v_pk_add_f32 v[82:83], v[82:83], v[238:239]
	v_cvt_pk_bf16_f32 v190, v92, v93
	v_cvt_pk_bf16_f32 v191, v94, v95
	v_cvt_pk_bf16_f32 v192, v88, v89
	v_cvt_pk_bf16_f32 v193, v90, v91
	v_cvt_pk_bf16_f32 v198, v84, v85
	v_cvt_pk_bf16_f32 v199, v86, v87
	v_cvt_pk_bf16_f32 v200, v80, v81
	v_cvt_pk_bf16_f32 v201, v82, v83
	ds_write_b128 v234, v[190:193]
	ds_read_b128 v[190:193], v235
	ds_write_b128 v234, v[198:201]
	ds_read_b128 v[198:201], v235
	v_mul_f32_e32 v203, v92, v92
	v_fmac_f32_e32 v203, v93, v93
	v_fmac_f32_e32 v203, v94, v94
	v_fmac_f32_e32 v203, v95, v95
	v_fmac_f32_e32 v203, v88, v88
	v_fmac_f32_e32 v203, v89, v89
	v_fmac_f32_e32 v203, v90, v90
	v_fmac_f32_e32 v203, v91, v91
	v_fmac_f32_e32 v203, v84, v84
	v_fmac_f32_e32 v203, v85, v85
	v_fmac_f32_e32 v203, v86, v86
	v_fmac_f32_e32 v203, v87, v87
	v_fmac_f32_e32 v203, v80, v80
	v_fmac_f32_e32 v203, v81, v81
	v_fmac_f32_e32 v203, v82, v82
	v_fmac_f32_e32 v203, v83, v83
	s_waitcnt lgkmcnt(2)
	global_store_dwordx4 v145, v[190:193], s[8:9]
	s_waitcnt lgkmcnt(0)
	global_store_dwordx4 v145, v[198:201], s[8:9] offset:256
	v_add_u32_e32 v145, 0x8000, v145
	global_load_dwordx4 v[190:193], v147, s[52:53] nt
	global_load_dwordx4 v[194:197], v144, s[52:53] nt
	global_load_dwordx4 v[198:201], v147, s[52:53] offset:512 nt
	global_load_dwordx4 v[206:209], v144, s[52:53] offset:512 nt
	v_add_u32_e32 v147, 0x10000, v147
	v_add_u32_e32 v144, 0x10000, v144
	s_waitcnt vmcnt(18)
	ds_write_b128 v226, v[210:213]
	s_mov_b64 exec, s[98:99]
	ds_read_b128 v[210:213], v227
	ds_read_b128 v[230:233], v228
	s_mov_b64 exec, -1
	ds_write_b128 v226, v[214:217]
	s_mov_b64 exec, s[100:101]
	ds_read_b128 v[210:213], v227
	ds_read_b128 v[230:233], v228
	s_mov_b64 exec, -1
	ds_write_b128 v226, v[218:221]
	s_mov_b64 exec, s[98:99]
	ds_read_b128 v[218:221], v227
	ds_read_b128 v[236:239], v228
	s_mov_b64 exec, -1
	ds_write_b128 v226, v[222:225]
	s_mov_b64 exec, s[100:101]
	ds_read_b128 v[218:221], v227
	ds_read_b128 v[236:239], v228
	s_mov_b64 exec, -1
	s_waitcnt lgkmcnt(6)
	v_pk_add_f32 v[76:77], v[76:77], v[210:211]
	v_pk_add_f32 v[78:79], v[78:79], v[212:213]
	v_pk_add_f32 v[72:73], v[72:73], v[230:231]
	v_pk_add_f32 v[74:75], v[74:75], v[232:233]
	s_waitcnt lgkmcnt(0)
; __device__ __forceinline__ u32x4 pack8(const float (&f)[8]) { u32x4 w; w.x = cvt_pk_bf16(f[0], f[1]); w.y = cvt_pk_bf16(f[2], f[3]); w.z = cvt_pk_bf16(f[4], f[5]); w.w = cvt_pk_bf16(f[6], f[7]); return w; }
;     __device__ __forceinline__ void operator()(const f32x4 (&acc)[2][2][4][2], const Unit& u, int wr, int wc, int fr, int fq) const {
;         const int row0 = u.pm * BM + wr * 64 + fr, col0 = u.pn * BM + wc * 32 + 8 * fq;
; #pragma unroll
;         for (int ai = 0; ai < 2; ++ai)
; #pragma unroll
;             for (int m = 0; m < 4; ++m) { const int row = row0 + ai * HALF + m * 16; const size_t idx = (size_t)row * 1024 + col0; float ss = 0.f;
; #pragma unroll
;                 for (int bj = 0; bj < 2; ++bj) { const f32x4 x0 = __builtin_nontemporal_load((const f32x4*)(x + idx + bj * HALF)), x1 = __builtin_nontemporal_load((const f32x4*)(x + idx + bj * HALF + 4));
;                     const f32x4 h0 = x0 + acc[ai][bj][m][0], h1v = x1 + acc[ai][bj][m][1];
;                     float f[8] = {h0[0], h0[1], h0[2], h0[3], h1v[0], h1v[1], h1v[2], h1v[3]};
; #pragma unroll
;                     for (int e = 0; e < 8; ++e) ss += f[e] * f[e];
;                     *(u32x4*)(h1b + idx + bj * HALF) = pack8(f); }
;                 ss += __shfl_xor(ss, 16); ss += __shfl_xor(ss, 32);
;                 if (fq == 0) atomicAdd(ssq + row, ss); }
	v_pk_add_f32 v[68:69], v[68:69], v[218:219]
	v_pk_add_f32 v[70:71], v[70:71], v[220:221]
	v_pk_add_f32 v[64:65], v[64:65], v[236:237]
	v_pk_add_f32 v[66:67], v[66:67], v[238:239]
	v_cvt_pk_bf16_f32 v210, v76, v77
	v_cvt_pk_bf16_f32 v211, v78, v79
	v_cvt_pk_bf16_f32 v212, v72, v73
	v_cvt_pk_bf16_f32 v213, v74, v75
	v_cvt_pk_bf16_f32 v218, v68, v69
	v_cvt_pk_bf16_f32 v219, v70, v71
	v_cvt_pk_bf16_f32 v220, v64, v65
	v_cvt_pk_bf16_f32 v221, v66, v67
	ds_write_b128 v234, v[210:213]
	ds_read_b128 v[210:213], v235
	ds_write_b128 v234, v[218:221]
	ds_read_b128 v[218:221], v235
	v_mul_f32_e32 v205, v76, v76
	v_fmac_f32_e32 v205, v77, v77
	v_fmac_f32_e32 v205, v78, v78
	v_fmac_f32_e32 v205, v79, v79
	v_fmac_f32_e32 v205, v72, v72
	v_fmac_f32_e32 v205, v73, v73
	v_fmac_f32_e32 v205, v74, v74
	v_fmac_f32_e32 v205, v75, v75
	v_fmac_f32_e32 v205, v68, v68
	v_fmac_f32_e32 v205, v69, v69
	v_fmac_f32_e32 v205, v70, v70
	v_fmac_f32_e32 v205, v71, v71
	v_fmac_f32_e32 v205, v64, v64
	v_fmac_f32_e32 v205, v65, v65
	v_fmac_f32_e32 v205, v66, v66
	v_fmac_f32_e32 v205, v67, v67
	s_waitcnt lgkmcnt(2)
	global_store_dwordx4 v145, v[210:213], s[8:9]
	s_waitcnt lgkmcnt(0)
	global_store_dwordx4 v145, v[218:221], s[8:9] offset:256
	v_add_u32_e32 v145, 0x28000, v145
	global_load_dwordx4 v[210:213], v147, s[52:53] nt
	global_load_dwordx4 v[214:217], v144, s[52:53] nt
	global_load_dwordx4 v[218:221], v147, s[52:53] offset:512 nt
	global_load_dwordx4 v[222:225], v144, s[52:53] offset:512 nt
	s_waitcnt vmcnt(18)
	ds_write_b128 v226, v[158:161]
	s_mov_b64 exec, s[98:99]
	ds_read_b128 v[158:161], v227
	ds_read_b128 v[230:233], v228
	s_mov_b64 exec, -1
	ds_write_b128 v226, v[162:165]
	s_mov_b64 exec, s[100:101]
	ds_read_b128 v[158:161], v227
	ds_read_b128 v[230:233], v228
	s_mov_b64 exec, -1
	ds_write_b128 v226, v[166:169]
	s_mov_b64 exec, s[98:99]
	ds_read_b128 v[166:169], v227
	ds_read_b128 v[236:239], v228
	s_mov_b64 exec, -1
	ds_write_b128 v226, v[170:173]
	s_mov_b64 exec, s[100:101]
	ds_read_b128 v[166:169], v227
	ds_read_b128 v[236:239], v228
	s_mov_b64 exec, -1
	s_waitcnt lgkmcnt(6)
	v_pk_add_f32 v[60:61], v[60:61], v[158:159]
	v_pk_add_f32 v[62:63], v[62:63], v[160:161]
	v_pk_add_f32 v[56:57], v[56:57], v[230:231]
	v_pk_add_f32 v[58:59], v[58:59], v[232:233]
	s_waitcnt lgkmcnt(0)
	v_pk_add_f32 v[52:53], v[52:53], v[166:167]
	v_pk_add_f32 v[54:55], v[54:55], v[168:169]
	v_pk_add_f32 v[48:49], v[48:49], v[236:237]
	v_pk_add_f32 v[50:51], v[50:51], v[238:239]
	v_cvt_pk_bf16_f32 v158, v60, v61
	v_cvt_pk_bf16_f32 v159, v62, v63
	v_cvt_pk_bf16_f32 v160, v56, v57
	v_cvt_pk_bf16_f32 v161, v58, v59
	v_cvt_pk_bf16_f32 v166, v52, v53
	v_cvt_pk_bf16_f32 v167, v54, v55
	v_cvt_pk_bf16_f32 v168, v48, v49
	v_cvt_pk_bf16_f32 v169, v50, v51
	ds_write_b128 v234, v[158:161]
	ds_read_b128 v[158:161], v235
	ds_write_b128 v234, v[166:169]
	ds_read_b128 v[166:169], v235
	v_mul_f32_e32 v242, v60, v60
	v_fmac_f32_e32 v242, v61, v61
	v_fmac_f32_e32 v242, v62, v62
	v_fmac_f32_e32 v242, v63, v63
	v_fmac_f32_e32 v242, v56, v56
	v_fmac_f32_e32 v242, v57, v57
	v_fmac_f32_e32 v242, v58, v58
	v_fmac_f32_e32 v242, v59, v59
	v_fmac_f32_e32 v242, v52, v52
	v_fmac_f32_e32 v242, v53, v53
	v_fmac_f32_e32 v242, v54, v54
	v_fmac_f32_e32 v242, v55, v55
	v_fmac_f32_e32 v242, v48, v48
	v_fmac_f32_e32 v242, v49, v49
	v_fmac_f32_e32 v242, v50, v50
	v_fmac_f32_e32 v242, v51, v51
	s_waitcnt lgkmcnt(2)
	global_store_dwordx4 v145, v[158:161], s[8:9]
	s_waitcnt lgkmcnt(0)
	global_store_dwordx4 v145, v[166:169], s[8:9] offset:256
	v_add_u32_e32 v145, 0x8000, v145
	s_waitcnt vmcnt(14)
	ds_write_b128 v226, v[174:177]
	s_mov_b64 exec, s[98:99]
	ds_read_b128 v[174:177], v227
	ds_read_b128 v[230:233], v228
	s_mov_b64 exec, -1
	ds_write_b128 v226, v[178:181]
	s_mov_b64 exec, s[100:101]
	ds_read_b128 v[174:177], v227
	ds_read_b128 v[230:233], v228
	s_mov_b64 exec, -1
	ds_write_b128 v226, v[182:185]
	s_mov_b64 exec, s[98:99]
	ds_read_b128 v[182:185], v227
	ds_read_b128 v[236:239], v228
	s_mov_b64 exec, -1
	ds_write_b128 v226, v[186:189]
	s_mov_b64 exec, s[100:101]
	ds_read_b128 v[182:185], v227
	ds_read_b128 v[236:239], v228
	s_mov_b64 exec, -1
	s_waitcnt lgkmcnt(6)
	v_pk_add_f32 v[44:45], v[44:45], v[174:175]
	v_pk_add_f32 v[46:47], v[46:47], v[176:177]
	v_pk_add_f32 v[40:41], v[40:41], v[230:231]
	v_pk_add_f32 v[42:43], v[42:43], v[232:233]
	s_waitcnt lgkmcnt(0)
	v_pk_add_f32 v[36:37], v[36:37], v[182:183]
	v_pk_add_f32 v[38:39], v[38:39], v[184:185]
	v_pk_add_f32 v[32:33], v[32:33], v[236:237]
	v_pk_add_f32 v[34:35], v[34:35], v[238:239]
	v_cvt_pk_bf16_f32 v174, v44, v45
	v_cvt_pk_bf16_f32 v175, v46, v47
	v_cvt_pk_bf16_f32 v176, v40, v41
	v_cvt_pk_bf16_f32 v177, v42, v43
	v_cvt_pk_bf16_f32 v182, v36, v37
	v_cvt_pk_bf16_f32 v183, v38, v39
	v_cvt_pk_bf16_f32 v184, v32, v33
	v_cvt_pk_bf16_f32 v185, v34, v35
	ds_write_b128 v234, v[174:177]
	ds_read_b128 v[174:177], v235
	ds_write_b128 v234, v[182:185]
	ds_read_b128 v[182:185], v235
	v_mul_f32_e32 v243, v44, v44
	v_fmac_f32_e32 v243, v45, v45
	v_fmac_f32_e32 v243, v46, v46
	v_fmac_f32_e32 v243, v47, v47
	v_fmac_f32_e32 v243, v40, v40
	v_fmac_f32_e32 v243, v41, v41
	v_fmac_f32_e32 v243, v42, v42
	v_fmac_f32_e32 v243, v43, v43
	v_fmac_f32_e32 v243, v36, v36
	v_fmac_f32_e32 v243, v37, v37
	v_fmac_f32_e32 v243, v38, v38
	v_fmac_f32_e32 v243, v39, v39
	v_fmac_f32_e32 v243, v32, v32
	v_fmac_f32_e32 v243, v33, v33
	v_fmac_f32_e32 v243, v34, v34
	v_fmac_f32_e32 v243, v35, v35
	s_waitcnt lgkmcnt(2)
	global_store_dwordx4 v145, v[174:177], s[8:9]
	s_waitcnt lgkmcnt(0)
	global_store_dwordx4 v145, v[182:185], s[8:9] offset:256
	v_add_u32_e32 v145, 0x8000, v145
	s_waitcnt vmcnt(10)
; __device__ __forceinline__ u32x4 pack8(const float (&f)[8]) { u32x4 w; w.x = cvt_pk_bf16(f[0], f[1]); w.y = cvt_pk_bf16(f[2], f[3]); w.z = cvt_pk_bf16(f[4], f[5]); w.w = cvt_pk_bf16(f[6], f[7]); return w; }
;     __device__ __forceinline__ void operator()(const f32x4 (&acc)[2][2][4][2], const Unit& u, int wr, int wc, int fr, int fq) const {
;         const int row0 = u.pm * BM + wr * 64 + fr, col0 = u.pn * BM + wc * 32 + 8 * fq;
; #pragma unroll
;         for (int ai = 0; ai < 2; ++ai)
; #pragma unroll
;             for (int m = 0; m < 4; ++m) { const int row = row0 + ai * HALF + m * 16; const size_t idx = (size_t)row * 1024 + col0; float ss = 0.f;
; #pragma unroll
;                 for (int bj = 0; bj < 2; ++bj) { const f32x4 x0 = __builtin_nontemporal_load((const f32x4*)(x + idx + bj * HALF)), x1 = __builtin_nontemporal_load((const f32x4*)(x + idx + bj * HALF + 4));
;                     const f32x4 h0 = x0 + acc[ai][bj][m][0], h1v = x1 + acc[ai][bj][m][1];
;                     float f[8] = {h0[0], h0[1], h0[2], h0[3], h1v[0], h1v[1], h1v[2], h1v[3]};
; #pragma unroll
;                     for (int e = 0; e < 8; ++e) ss += f[e] * f[e];
;                     *(u32x4*)(h1b + idx + bj * HALF) = pack8(f); }
;                 ss += __shfl_xor(ss, 16); ss += __shfl_xor(ss, 32);
;                 if (fq == 0) atomicAdd(ssq + row, ss); }
	ds_write_b128 v226, v[190:193]
	s_mov_b64 exec, s[98:99]
	ds_read_b128 v[190:193], v227
	ds_read_b128 v[230:233], v228
	s_mov_b64 exec, -1
	ds_write_b128 v226, v[194:197]
	s_mov_b64 exec, s[100:101]
	ds_read_b128 v[190:193], v227
	ds_read_b128 v[230:233], v228
	s_mov_b64 exec, -1
	ds_write_b128 v226, v[198:201]
	s_mov_b64 exec, s[98:99]
	ds_read_b128 v[198:201], v227
	ds_read_b128 v[236:239], v228
	s_mov_b64 exec, -1
	ds_write_b128 v226, v[206:209]
	s_mov_b64 exec, s[100:101]
	ds_read_b128 v[198:201], v227
	ds_read_b128 v[236:239], v228
	s_mov_b64 exec, -1
	s_waitcnt lgkmcnt(6)
	v_pk_add_f32 v[28:29], v[28:29], v[190:191]
	v_pk_add_f32 v[30:31], v[30:31], v[192:193]
	v_pk_add_f32 v[24:25], v[24:25], v[230:231]
	v_pk_add_f32 v[26:27], v[26:27], v[232:233]
	s_waitcnt lgkmcnt(0)
	v_pk_add_f32 v[20:21], v[20:21], v[198:199]
	v_pk_add_f32 v[22:23], v[22:23], v[200:201]
	v_pk_add_f32 v[16:17], v[16:17], v[236:237]
	v_pk_add_f32 v[18:19], v[18:19], v[238:239]
	v_cvt_pk_bf16_f32 v190, v28, v29
	v_cvt_pk_bf16_f32 v191, v30, v31
	v_cvt_pk_bf16_f32 v192, v24, v25
	v_cvt_pk_bf16_f32 v193, v26, v27
	v_cvt_pk_bf16_f32 v198, v20, v21
	v_cvt_pk_bf16_f32 v199, v22, v23
	v_cvt_pk_bf16_f32 v200, v16, v17
	v_cvt_pk_bf16_f32 v201, v18, v19
	ds_write_b128 v234, v[190:193]
	ds_read_b128 v[190:193], v235
	ds_write_b128 v234, v[198:201]
	ds_read_b128 v[198:201], v235
	v_mul_f32_e32 v244, v28, v28
	v_fmac_f32_e32 v244, v29, v29
	v_fmac_f32_e32 v244, v30, v30
	v_fmac_f32_e32 v244, v31, v31
	v_fmac_f32_e32 v244, v24, v24
	v_fmac_f32_e32 v244, v25, v25
	v_fmac_f32_e32 v244, v26, v26
	v_fmac_f32_e32 v244, v27, v27
	v_fmac_f32_e32 v244, v20, v20
	v_fmac_f32_e32 v244, v21, v21
	v_fmac_f32_e32 v244, v22, v22
	v_fmac_f32_e32 v244, v23, v23
	v_fmac_f32_e32 v244, v16, v16
	v_fmac_f32_e32 v244, v17, v17
	v_fmac_f32_e32 v244, v18, v18
	v_fmac_f32_e32 v244, v19, v19
	s_waitcnt lgkmcnt(2)
	global_store_dwordx4 v145, v[190:193], s[8:9]
	s_waitcnt lgkmcnt(0)
	global_store_dwordx4 v145, v[198:201], s[8:9] offset:256
	v_add_u32_e32 v145, 0x8000, v145
	s_waitcnt vmcnt(6)
	ds_write_b128 v226, v[210:213]
	s_mov_b64 exec, s[98:99]
	ds_read_b128 v[210:213], v227
	ds_read_b128 v[230:233], v228
	s_mov_b64 exec, -1
	ds_write_b128 v226, v[214:217]
	s_mov_b64 exec, s[100:101]
	ds_read_b128 v[210:213], v227
	ds_read_b128 v[230:233], v228
	s_mov_b64 exec, -1
	ds_write_b128 v226, v[218:221]
	s_mov_b64 exec, s[98:99]
	ds_read_b128 v[218:221], v227
	ds_read_b128 v[236:239], v228
	s_mov_b64 exec, -1
	ds_write_b128 v226, v[222:225]
	s_mov_b64 exec, s[100:101]
	ds_read_b128 v[218:221], v227
	ds_read_b128 v[236:239], v228
	s_mov_b64 exec, -1
	s_waitcnt lgkmcnt(6)
	v_pk_add_f32 v[12:13], v[12:13], v[210:211]
	v_pk_add_f32 v[14:15], v[14:15], v[212:213]
	v_pk_add_f32 v[8:9], v[8:9], v[230:231]
	v_pk_add_f32 v[10:11], v[10:11], v[232:233]
	s_waitcnt lgkmcnt(0)
	v_pk_add_f32 v[4:5], v[4:5], v[218:219]
	v_pk_add_f32 v[6:7], v[6:7], v[220:221]
	v_pk_add_f32 v[0:1], v[0:1], v[236:237]
	v_pk_add_f32 v[2:3], v[2:3], v[238:239]
	v_cvt_pk_bf16_f32 v210, v12, v13
	v_cvt_pk_bf16_f32 v211, v14, v15
	v_cvt_pk_bf16_f32 v212, v8, v9
	v_cvt_pk_bf16_f32 v213, v10, v11
	v_cvt_pk_bf16_f32 v218, v4, v5
	v_cvt_pk_bf16_f32 v219, v6, v7
	v_cvt_pk_bf16_f32 v220, v0, v1
	v_cvt_pk_bf16_f32 v221, v2, v3
	ds_write_b128 v234, v[210:213]
	ds_read_b128 v[210:213], v235
	ds_write_b128 v234, v[218:221]
	ds_read_b128 v[218:221], v235
	v_mul_f32_e32 v245, v12, v12
	v_fmac_f32_e32 v245, v13, v13
	v_fmac_f32_e32 v245, v14, v14
	v_fmac_f32_e32 v245, v15, v15
	v_fmac_f32_e32 v245, v8, v8
	v_fmac_f32_e32 v245, v9, v9
	v_fmac_f32_e32 v245, v10, v10
	v_fmac_f32_e32 v245, v11, v11
	v_fmac_f32_e32 v245, v4, v4
	v_fmac_f32_e32 v245, v5, v5
	v_fmac_f32_e32 v245, v6, v6
	v_fmac_f32_e32 v245, v7, v7
	v_fmac_f32_e32 v245, v0, v0
	v_fmac_f32_e32 v245, v1, v1
	v_fmac_f32_e32 v245, v2, v2
	v_fmac_f32_e32 v245, v3, v3
	s_waitcnt lgkmcnt(2)
	global_store_dwordx4 v145, v[210:213], s[8:9]
	s_waitcnt lgkmcnt(0)
	global_store_dwordx4 v145, v[218:221], s[8:9] offset:256
	v_xor_b32_e32 v158, 16, v156
	v_xor_b32_e32 v159, 32, v156
	v_lshlrev_b32_e32 v158, 2, v158
	v_lshlrev_b32_e32 v159, 2, v159
	ds_bpermute_b32 v162, v158, v157
	ds_bpermute_b32 v163, v158, v202
	ds_bpermute_b32 v164, v158, v203
	ds_bpermute_b32 v165, v158, v205
	ds_bpermute_b32 v166, v158, v242
	ds_bpermute_b32 v167, v158, v243
	ds_bpermute_b32 v168, v158, v244
	ds_bpermute_b32 v169, v158, v245
	s_waitcnt lgkmcnt(0)
	v_add_f32_e32 v157, v157, v162
	v_add_f32_e32 v202, v202, v163
	v_add_f32_e32 v203, v203, v164
	v_add_f32_e32 v205, v205, v165
	v_add_f32_e32 v242, v242, v166
	v_add_f32_e32 v243, v243, v167
	v_add_f32_e32 v244, v244, v168
	v_add_f32_e32 v245, v245, v169
	ds_bpermute_b32 v162, v159, v157
	ds_bpermute_b32 v163, v159, v202
	ds_bpermute_b32 v164, v159, v203
	ds_bpermute_b32 v165, v159, v205
	ds_bpermute_b32 v166, v159, v242
	ds_bpermute_b32 v167, v159, v243
	ds_bpermute_b32 v168, v159, v244
	ds_bpermute_b32 v169, v159, v245
	s_waitcnt lgkmcnt(0)
	v_add_f32_e32 v157, v157, v162
	v_add_f32_e32 v202, v202, v163
	v_add_f32_e32 v203, v203, v164
	v_add_f32_e32 v205, v205, v165
	v_add_f32_e32 v242, v242, v166
	v_add_f32_e32 v243, v243, v167
	v_add_f32_e32 v244, v244, v168
	v_add_f32_e32 v245, v245, v169
	s_and_saveexec_b64 s[44:45], s[4:5]
	global_atomic_add_f32 v149, v157, s[68:69]
	global_atomic_add_f32 v149, v202, s[68:69] offset:64
	global_atomic_add_f32 v149, v203, s[68:69] offset:128
	global_atomic_add_f32 v149, v205, s[68:69] offset:192
	global_atomic_add_f32 v149, v242, s[68:69] offset:512
	global_atomic_add_f32 v149, v243, s[68:69] offset:576
	global_atomic_add_f32 v149, v244, s[68:69] offset:640
	global_atomic_add_f32 v149, v245, s[68:69] offset:704
	s_or_b64 exec, exec, s[44:45]
	s_andn2_b64 vcc, exec, s[6:7]
	s_mov_b64 s[6:7], -1
	s_cbranch_vccnz .LBB0_637
	s_andn2_b64 vcc, exec, s[12:13]
	s_cbranch_vccnz .LBB0_636
	s_barrier
	s_branch .LBB0_636
